# instruction selection in the VALU-bound scan: producer fetch uses one running 64-bit address per tensor (v_lshl_add_u64) instead of add_co/nop/addc per load
# speedup vs baseline: 1.0059x; 1.0059x over previous
; __device__ __forceinline__ void ck_fetch(CkRaw& x, const bf16_t* R, const bf16_t* K, const bf16_t* V, const bf16_t* LDh, const bf16_t* Ah, size_t rowbase, int lane) {
; #pragma unroll
;     for (int t = 0; t < 16; ++t) { const size_t off = rowbase + (size_t)t * DM + lane; x.r[t] = R[off]; x.k[t] = K[off]; x.v[t] = V[off]; x.l[t] = LDh[off]; x.a[t] = Ah[off]; }
; }
.LBB0_183:
	v_lshl_add_u64 v[32:33], v[36:37], 0, s[18:19]
	v_mov_b32_e32 v172, 0x1000
	v_mov_b32_e32 v173, 0
	v_add_co_u32_e32 v130, vcc, 0xe740000, v32
	s_nop 1
	v_addc_co_u32_e32 v131, vcc, 0, v33, vcc
	global_load_ushort v51, v[130:131], off
	v_add_co_u32_e32 v134, vcc, 0x12740000, v32
	s_nop 1
	v_addc_co_u32_e32 v135, vcc, 0, v33, vcc
	global_load_ushort v52, v[134:135], off
	v_add_co_u32_e32 v136, vcc, 0x16740000, v32
	s_nop 1
	v_addc_co_u32_e32 v137, vcc, 0, v33, vcc
	global_load_ushort v53, v[136:137], off
	v_add_co_u32_e32 v162, vcc, 0x2740000, v32
	s_nop 1
	v_addc_co_u32_e32 v163, vcc, 0, v33, vcc
	global_load_ushort v59, v[162:163], off
	v_add_co_u32_e32 v164, vcc, 0x6740000, v32
	s_nop 1
	v_addc_co_u32_e32 v165, vcc, 0, v33, vcc
	global_load_ushort v60, v[164:165], off
	v_lshl_add_u64 v[130:131], v[130:131], 0, v[172:173]
	global_load_ushort v61, v[130:131], off
	v_lshl_add_u64 v[134:135], v[134:135], 0, v[172:173]
	global_load_ushort v62, v[134:135], off
	v_lshl_add_u64 v[136:137], v[136:137], 0, v[172:173]
	global_load_ushort v63, v[136:137], off
	v_lshl_add_u64 v[162:163], v[162:163], 0, v[172:173]
	global_load_ushort v64, v[162:163], off
	v_lshl_add_u64 v[164:165], v[164:165], 0, v[172:173]
	global_load_ushort v65, v[164:165], off
	v_lshl_add_u64 v[130:131], v[130:131], 0, v[172:173]
	global_load_ushort v66, v[130:131], off
	v_lshl_add_u64 v[134:135], v[134:135], 0, v[172:173]
	global_load_ushort v67, v[134:135], off
	v_lshl_add_u64 v[136:137], v[136:137], 0, v[172:173]
	global_load_ushort v68, v[136:137], off
	v_lshl_add_u64 v[162:163], v[162:163], 0, v[172:173]
	global_load_ushort v69, v[162:163], off
	v_lshl_add_u64 v[164:165], v[164:165], 0, v[172:173]
	global_load_ushort v70, v[164:165], off
	v_lshl_add_u64 v[130:131], v[130:131], 0, v[172:173]
	global_load_ushort v71, v[130:131], off
	v_lshl_add_u64 v[134:135], v[134:135], 0, v[172:173]
	global_load_ushort v72, v[134:135], off
	v_lshl_add_u64 v[136:137], v[136:137], 0, v[172:173]
	global_load_ushort v73, v[136:137], off
	v_lshl_add_u64 v[162:163], v[162:163], 0, v[172:173]
	global_load_ushort v74, v[162:163], off
	v_lshl_add_u64 v[164:165], v[164:165], 0, v[172:173]
	global_load_ushort v75, v[164:165], off
	v_lshl_add_u64 v[130:131], v[130:131], 0, v[172:173]
	global_load_ushort v76, v[130:131], off
	v_lshl_add_u64 v[134:135], v[134:135], 0, v[172:173]
	global_load_ushort v77, v[134:135], off
	v_lshl_add_u64 v[136:137], v[136:137], 0, v[172:173]
	global_load_ushort v78, v[136:137], off
	v_lshl_add_u64 v[162:163], v[162:163], 0, v[172:173]
	global_load_ushort v79, v[162:163], off
	v_lshl_add_u64 v[164:165], v[164:165], 0, v[172:173]
	global_load_ushort v80, v[164:165], off
	v_lshl_add_u64 v[130:131], v[130:131], 0, v[172:173]
	global_load_ushort v81, v[130:131], off
	v_lshl_add_u64 v[134:135], v[134:135], 0, v[172:173]
	global_load_ushort v82, v[134:135], off
	v_lshl_add_u64 v[136:137], v[136:137], 0, v[172:173]
	global_load_ushort v83, v[136:137], off
	v_lshl_add_u64 v[162:163], v[162:163], 0, v[172:173]
	global_load_ushort v84, v[162:163], off
	v_lshl_add_u64 v[164:165], v[164:165], 0, v[172:173]
	global_load_ushort v85, v[164:165], off
	v_lshl_add_u64 v[130:131], v[130:131], 0, v[172:173]
	global_load_ushort v86, v[130:131], off
	v_lshl_add_u64 v[134:135], v[134:135], 0, v[172:173]
	global_load_ushort v87, v[134:135], off
	v_lshl_add_u64 v[136:137], v[136:137], 0, v[172:173]
	global_load_ushort v88, v[136:137], off
	v_lshl_add_u64 v[162:163], v[162:163], 0, v[172:173]
	global_load_ushort v89, v[162:163], off
	v_lshl_add_u64 v[164:165], v[164:165], 0, v[172:173]
	global_load_ushort v90, v[164:165], off
	v_lshl_add_u64 v[130:131], v[130:131], 0, v[172:173]
	global_load_ushort v91, v[130:131], off
	v_lshl_add_u64 v[134:135], v[134:135], 0, v[172:173]
	global_load_ushort v92, v[134:135], off
	v_lshl_add_u64 v[136:137], v[136:137], 0, v[172:173]
	global_load_ushort v93, v[136:137], off
	v_lshl_add_u64 v[162:163], v[162:163], 0, v[172:173]
; __device__ __forceinline__ void ck_fetch(CkRaw& x, const bf16_t* R, const bf16_t* K, const bf16_t* V, const bf16_t* LDh, const bf16_t* Ah, size_t rowbase, int lane) {
; #pragma unroll
;     for (int t = 0; t < 16; ++t) { const size_t off = rowbase + (size_t)t * DM + lane; x.r[t] = R[off]; x.k[t] = K[off]; x.v[t] = V[off]; x.l[t] = LDh[off]; x.a[t] = Ah[off]; }
; }
	global_load_ushort v94, v[162:163], off
	v_lshl_add_u64 v[164:165], v[164:165], 0, v[172:173]
	global_load_ushort v95, v[164:165], off
	v_lshl_add_u64 v[130:131], v[130:131], 0, v[172:173]
	global_load_ushort v96, v[130:131], off
	v_lshl_add_u64 v[134:135], v[134:135], 0, v[172:173]
	global_load_ushort v97, v[134:135], off
	v_lshl_add_u64 v[136:137], v[136:137], 0, v[172:173]
	global_load_ushort v98, v[136:137], off
	v_lshl_add_u64 v[162:163], v[162:163], 0, v[172:173]
	global_load_ushort v99, v[162:163], off
	v_lshl_add_u64 v[164:165], v[164:165], 0, v[172:173]
	global_load_ushort v100, v[164:165], off
	v_lshl_add_u64 v[130:131], v[130:131], 0, v[172:173]
	global_load_ushort v101, v[130:131], off
	v_lshl_add_u64 v[134:135], v[134:135], 0, v[172:173]
	global_load_ushort v102, v[134:135], off
	v_lshl_add_u64 v[136:137], v[136:137], 0, v[172:173]
	global_load_ushort v103, v[136:137], off
	v_lshl_add_u64 v[162:163], v[162:163], 0, v[172:173]
	global_load_ushort v104, v[162:163], off
	v_lshl_add_u64 v[164:165], v[164:165], 0, v[172:173]
	global_load_ushort v105, v[164:165], off
	v_lshl_add_u64 v[130:131], v[130:131], 0, v[172:173]
	global_load_ushort v106, v[130:131], off
	v_lshl_add_u64 v[134:135], v[134:135], 0, v[172:173]
	global_load_ushort v107, v[134:135], off
	v_lshl_add_u64 v[136:137], v[136:137], 0, v[172:173]
	global_load_ushort v108, v[136:137], off
	v_lshl_add_u64 v[162:163], v[162:163], 0, v[172:173]
	global_load_ushort v109, v[162:163], off
	v_lshl_add_u64 v[164:165], v[164:165], 0, v[172:173]
	global_load_ushort v110, v[164:165], off
	v_lshl_add_u64 v[130:131], v[130:131], 0, v[172:173]
	global_load_ushort v111, v[130:131], off
	v_lshl_add_u64 v[134:135], v[134:135], 0, v[172:173]
	global_load_ushort v112, v[134:135], off
	v_lshl_add_u64 v[136:137], v[136:137], 0, v[172:173]
	global_load_ushort v113, v[136:137], off
	v_lshl_add_u64 v[162:163], v[162:163], 0, v[172:173]
	global_load_ushort v114, v[162:163], off
	v_lshl_add_u64 v[164:165], v[164:165], 0, v[172:173]
	global_load_ushort v115, v[164:165], off
	v_lshl_add_u64 v[130:131], v[130:131], 0, v[172:173]
	global_load_ushort v116, v[130:131], off
	v_lshl_add_u64 v[134:135], v[134:135], 0, v[172:173]
	global_load_ushort v117, v[134:135], off
	v_lshl_add_u64 v[136:137], v[136:137], 0, v[172:173]
	global_load_ushort v118, v[136:137], off
	v_lshl_add_u64 v[162:163], v[162:163], 0, v[172:173]
	global_load_ushort v119, v[162:163], off
	v_lshl_add_u64 v[164:165], v[164:165], 0, v[172:173]
	global_load_ushort v120, v[164:165], off
	v_lshl_add_u64 v[130:131], v[130:131], 0, v[172:173]
	global_load_ushort v121, v[130:131], off
	v_lshl_add_u64 v[134:135], v[134:135], 0, v[172:173]
	global_load_ushort v122, v[134:135], off
	v_lshl_add_u64 v[136:137], v[136:137], 0, v[172:173]
	global_load_ushort v123, v[136:137], off
	v_lshl_add_u64 v[162:163], v[162:163], 0, v[172:173]
	global_load_ushort v124, v[162:163], off
	v_lshl_add_u64 v[164:165], v[164:165], 0, v[172:173]
	global_load_ushort v125, v[164:165], off
	v_lshl_add_u64 v[130:131], v[130:131], 0, v[172:173]
	global_load_ushort v139, v[130:131], off
	v_lshl_add_u64 v[134:135], v[134:135], 0, v[172:173]
	global_load_ushort v141, v[134:135], off
	v_lshl_add_u64 v[136:137], v[136:137], 0, v[172:173]
	global_load_ushort v143, v[136:137], off
	v_lshl_add_u64 v[162:163], v[162:163], 0, v[172:173]
	global_load_ushort v145, v[162:163], off
	v_lshl_add_u64 v[164:165], v[164:165], 0, v[172:173]
	global_load_ushort v154, v[164:165], off
	v_lshl_add_u64 v[130:131], v[130:131], 0, v[172:173]
	global_load_ushort v155, v[130:131], off
	v_lshl_add_u64 v[134:135], v[134:135], 0, v[172:173]
	global_load_ushort v156, v[134:135], off
	v_lshl_add_u64 v[136:137], v[136:137], 0, v[172:173]
	global_load_ushort v157, v[136:137], off
	v_lshl_add_u64 v[162:163], v[162:163], 0, v[172:173]
	global_load_ushort v158, v[162:163], off
	v_lshl_add_u64 v[164:165], v[164:165], 0, v[172:173]
	global_load_ushort v159, v[164:165], off
	s_branch .LBB0_167
